# G1/G3 K-loop bottom: s_setprio 0 moved after the SALU pointer updates (wave keeps MFMA priority until it reaches the barrier)
# speedup vs baseline: 1.0044x; 1.0014x over previous
; #define PG8_STAGE(bufoff, gbase, voff) do { _Pragma("unroll") for (int _i = 0; _i < 2; ++_i) \
;         __builtin_amdgcn_global_load_lds((const unsigned*)((const char*)(gbase) + (voff)[_i]), (PG8_LAS unsigned*)(lds + (bufoff) + ldsw + _i * 8192), 16, 0, 0); } while (0)
; #define PG8_LDA(dst, b, h) do { _Pragma("unroll") for (int m = 0; m < 4; ++m) _Pragma("unroll") for (int k = 0; k < 2; ++k) dst[m][k] = *(const PG8_LAS bf16x8*)(lds + PG8_SA(b, h) + aoff + m * 2048 + k * 1024); } while (0)
; #define PG8_LDB(dst, b, h) do { _Pragma("unroll") for (int n = 0; n < 2; ++n) _Pragma("unroll") for (int k = 0; k < 2; ++k) dst[n][k] = *(const PG8_LAS bf16x8*)(lds + PG8_SB(b, h) + boff + n * 2048 + k * 1024); } while (0)
; #define PG8_MMA(ai, bj, At, Bt) do { __builtin_amdgcn_s_setprio(1); _Pragma("unroll") for (int m = 0; m < 4; ++m) _Pragma("unroll") for (int n = 0; n < 2; ++n) _Pragma("unroll") for (int k = 0; k < 2; ++k) \
;         acc[ai][bj][m][n] = __builtin_amdgcn_mfma_f32_16x16x32_bf16(Bt[n][k], At[m][k], acc[ai][bj][m][n], 0, 0, 0); __builtin_amdgcn_s_setprio(0); } while (0)
; #define PG8_WAIT_V(n) asm volatile("s_waitcnt vmcnt(" #n ")" ::: "memory")
; template <class Epi, class Sched, bool ALIGN_EPI = false, bool SP2 = false>
; __device__ __forceinline__ void gemm_phase(PG8_LAS unsigned char* lds, const Gemm g, const Sched& S, const Epi& E) {
;     ...
;             const bool last = (t == nt - 2);
;             const char* a1 = cA + (size_t)(t + 1) * kstep;
;             const char* a2 = last ? nA : cA + (size_t)(t + 2) * kstep; const char* b2 = last ? nB : cB + (size_t)(t + 2) * kstep;
;             const char* a3 = a2 + kstep; const char* b3 = b2 + kstep;
;             if (last && has_next) S.a_ready(nxt);
;             if constexpr (Epi::MID) { if (t == nt / 2) E.mid(acc, cur, wr, wc, fr, fq); }
;             if constexpr (SP2) {
;             PG8_LDB(B0, 0, 0); PG8_LDB(B1, 0, 1); PG8_SCHED; PG8_LDA(At, 0, 0); PG8_STAGE(PG8_SA(1, 1), a1 + hstep, voffA);
;             PG8_WAIT_V(8); PG8_WAIT_L(0); PG8_BAR; PG8_MMA(0, 0, At, B0); PG8_MMA(0, 1, At, B1); PG8_BAR; PG8_SCHED;
;             PG8_LDA(At, 0, 1); PG8_STAGE(PG8_SB(0, 0), b2, voffB); PG8_STAGE(PG8_SB(0, 1), b2 + hstep, voffB); PG8_STAGE(PG8_SA(0, 0), a2, voffA);
;             PG8_WAIT_V(8); PG8_WAIT_L(0); PG8_BAR; PG8_MMA(1, 0, At, B0); PG8_MMA(1, 1, At, B1); PG8_BAR; PG8_SCHED;
.LBB0_38:
	s_add_u32 s62, s60, 0xfff80080
	s_addc_u32 s63, s61, -1
	s_add_i32 s86, 0, 0x10000
	s_cmp_eq_u32 s83, 28
	s_cselect_b32 s65, s2, s63
	s_cselect_b32 s64, s3, s62
	v_add_u32_e32 v142, s86, v156
	s_cselect_b32 s63, s53, s82
	s_cselect_b32 s62, s55, s79
	s_add_i32 s88, 0, 0x14000
	ds_read_b128 v[152:155], v142
	ds_read_b128 v[160:163], v142 offset:1024
	ds_read_b128 v[164:167], v142 offset:2048
	ds_read_b128 v[182:185], v142 offset:3072
	v_add_u32_e32 v142, s88, v156
	ds_read_b128 v[186:189], v142
	ds_read_b128 v[190:193], v142 offset:1024
	ds_read_b128 v[194:197], v142 offset:2048
	ds_read_b128 v[198:201], v142 offset:3072
	v_lshl_add_u64 v[142:143], s[60:61], 0, v[150:151]
	s_add_i32 m0, s69, 0xc000
	ds_read_b128 v[202:205], v158
	ds_read_b128 v[206:209], v158 offset:1024
	ds_read_b128 v[214:217], v158 offset:2048
	ds_read_b128 v[218:221], v158 offset:3072
	ds_read_b128 v[222:225], v158 offset:4096
	ds_read_b128 v[226:229], v158 offset:5120
	ds_read_b128 v[230:233], v158 offset:6144
	ds_read_b128 v[234:237], v158 offset:7168
	global_load_lds_dwordx4 v[142:143], off
	v_lshl_add_u64 v[142:143], s[60:61], 0, v[136:137]
	s_add_i32 m0, s69, 0xe000
	s_nop 0
	global_load_lds_dwordx4 v[142:143], off
	s_waitcnt vmcnt(8)
	s_waitcnt lgkmcnt(0)
	s_setprio 1
	s_barrier
	v_mfma_f32_16x16x32_bf16 v[126:129], v[152:155], v[202:205], v[126:129]
	v_mfma_f32_16x16x32_bf16 v[122:125], v[164:167], v[202:205], v[122:125]
	v_mfma_f32_16x16x32_bf16 v[110:113], v[152:155], v[214:217], v[110:113]
	v_mfma_f32_16x16x32_bf16 v[106:109], v[164:167], v[214:217], v[106:109]
	v_mfma_f32_16x16x32_bf16 v[94:97], v[152:155], v[222:225], v[94:97]
	v_mfma_f32_16x16x32_bf16 v[90:93], v[164:167], v[222:225], v[90:93]
	v_mfma_f32_16x16x32_bf16 v[78:81], v[152:155], v[230:233], v[78:81]
	v_mfma_f32_16x16x32_bf16 v[74:77], v[164:167], v[230:233], v[74:77]
	v_mfma_f32_16x16x32_bf16 v[126:129], v[160:163], v[206:209], v[126:129]
	v_mfma_f32_16x16x32_bf16 v[122:125], v[182:185], v[206:209], v[122:125]
	v_mfma_f32_16x16x32_bf16 v[110:113], v[160:163], v[218:221], v[110:113]
	v_mfma_f32_16x16x32_bf16 v[106:109], v[182:185], v[218:221], v[106:109]
	v_mfma_f32_16x16x32_bf16 v[94:97], v[160:163], v[226:229], v[94:97]
	v_mfma_f32_16x16x32_bf16 v[90:93], v[182:185], v[226:229], v[90:93]
	v_mfma_f32_16x16x32_bf16 v[78:81], v[160:163], v[234:237], v[78:81]
	v_mfma_f32_16x16x32_bf16 v[74:77], v[182:185], v[234:237], v[74:77]
	s_setprio 0
	s_setprio 1
	v_mfma_f32_16x16x32_bf16 v[118:121], v[186:189], v[202:205], v[118:121]
	v_mfma_f32_16x16x32_bf16 v[114:117], v[194:197], v[202:205], v[114:117]
	v_mfma_f32_16x16x32_bf16 v[102:105], v[186:189], v[214:217], v[102:105]
	v_mfma_f32_16x16x32_bf16 v[98:101], v[194:197], v[214:217], v[98:101]
	v_mfma_f32_16x16x32_bf16 v[86:89], v[186:189], v[222:225], v[86:89]
	v_mfma_f32_16x16x32_bf16 v[82:85], v[194:197], v[222:225], v[82:85]
	v_mfma_f32_16x16x32_bf16 v[70:73], v[186:189], v[230:233], v[70:73]
	v_mfma_f32_16x16x32_bf16 v[66:69], v[194:197], v[230:233], v[66:69]
	v_mfma_f32_16x16x32_bf16 v[118:121], v[190:193], v[206:209], v[118:121]
	v_mfma_f32_16x16x32_bf16 v[114:117], v[198:201], v[206:209], v[114:117]
	v_mfma_f32_16x16x32_bf16 v[102:105], v[190:193], v[218:221], v[102:105]
	v_mfma_f32_16x16x32_bf16 v[98:101], v[198:201], v[218:221], v[98:101]
	v_mfma_f32_16x16x32_bf16 v[86:89], v[190:193], v[226:229], v[86:89]
	v_mfma_f32_16x16x32_bf16 v[82:85], v[198:201], v[226:229], v[82:85]
	v_mfma_f32_16x16x32_bf16 v[70:73], v[190:193], v[234:237], v[70:73]
	v_mfma_f32_16x16x32_bf16 v[66:69], v[198:201], v[234:237], v[66:69]
	s_setprio 0
	s_barrier
	s_add_i32 s86, s86, s68
	v_lshl_add_u64 v[142:143], s[62:63], 0, v[0:1]
	s_mov_b32 m0, s86
	ds_read_b128 v[202:205], v158 offset:16384
	ds_read_b128 v[206:209], v158 offset:17408
	ds_read_b128 v[214:217], v158 offset:18432
	ds_read_b128 v[218:221], v158 offset:19456
	ds_read_b128 v[222:225], v158 offset:20480
	ds_read_b128 v[226:229], v158 offset:21504
	ds_read_b128 v[230:233], v158 offset:22528
	ds_read_b128 v[234:237], v158 offset:23552
	global_load_lds_dwordx4 v[142:143], off
	s_add_i32 m0, s86, 0x2000
	s_add_u32 s86, s62, 0x80000
	v_lshl_add_u64 v[144:145], s[62:63], 0, v[130:131]
	s_addc_u32 s87, s63, 0
	s_add_i32 s88, s88, s68
	global_load_lds_dwordx4 v[144:145], off
	v_lshl_add_u64 v[168:169], s[86:87], 0, v[0:1]
	s_mov_b32 m0, s88
	v_lshl_add_u64 v[238:239], s[64:65], 0, v[132:133]
	global_load_lds_dwordx4 v[168:169], off
	v_lshl_add_u64 v[168:169], s[86:87], 0, v[130:131]
	s_add_i32 m0, s88, 0x2000
	s_nop 0
	global_load_lds_dwordx4 v[168:169], off
	v_lshl_add_u64 v[168:169], s[64:65], 0, v[134:135]
	s_mov_b32 m0, s69
	s_nop 0
	global_load_lds_dwordx4 v[168:169], off
	s_mov_b32 m0, s70
	s_nop 0
	global_load_lds_dwordx4 v[238:239], off
	s_waitcnt vmcnt(8)
	s_waitcnt lgkmcnt(0)
	s_setprio 1
	s_barrier
; #define PG8_STAGE(bufoff, gbase, voff) do { _Pragma("unroll") for (int _i = 0; _i < 2; ++_i) \
;         __builtin_amdgcn_global_load_lds((const unsigned*)((const char*)(gbase) + (voff)[_i]), (PG8_LAS unsigned*)(lds + (bufoff) + ldsw + _i * 8192), 16, 0, 0); } while (0)
; #define PG8_LDA(dst, b, h) do { _Pragma("unroll") for (int m = 0; m < 4; ++m) _Pragma("unroll") for (int k = 0; k < 2; ++k) dst[m][k] = *(const PG8_LAS bf16x8*)(lds + PG8_SA(b, h) + aoff + m * 2048 + k * 1024); } while (0)
; #define PG8_LDB(dst, b, h) do { _Pragma("unroll") for (int n = 0; n < 2; ++n) _Pragma("unroll") for (int k = 0; k < 2; ++k) dst[n][k] = *(const PG8_LAS bf16x8*)(lds + PG8_SB(b, h) + boff + n * 2048 + k * 1024); } while (0)
; #define PG8_MMA(ai, bj, At, Bt) do { __builtin_amdgcn_s_setprio(1); _Pragma("unroll") for (int m = 0; m < 4; ++m) _Pragma("unroll") for (int n = 0; n < 2; ++n) _Pragma("unroll") for (int k = 0; k < 2; ++k) \
;         acc[ai][bj][m][n] = __builtin_amdgcn_mfma_f32_16x16x32_bf16(Bt[n][k], At[m][k], acc[ai][bj][m][n], 0, 0, 0); __builtin_amdgcn_s_setprio(0); } while (0)
; #define PG8_WAIT_V(n) asm volatile("s_waitcnt vmcnt(" #n ")" ::: "memory")
; #define PG8_WAIT_L(n) asm volatile("s_waitcnt lgkmcnt(" #n ")" ::: "memory")
; #define PG8_BAR __builtin_amdgcn_s_barrier()
; #define PG8_SCHED __builtin_amdgcn_sched_barrier(0)
; template <class Epi, class Sched, bool ALIGN_EPI = false, bool SP2 = false>
; __device__ __forceinline__ void gemm_phase(PG8_LAS unsigned char* lds, const Gemm g, const Sched& S, const Epi& E) {
;     ...
;             PG8_WAIT_V(8); PG8_WAIT_L(0); PG8_BAR; PG8_MMA(1, 0, At, B0); PG8_MMA(1, 1, At, B1); PG8_BAR; PG8_SCHED;
;             PG8_LDB(B0, 1, 0); PG8_LDB(B1, 1, 1); PG8_SCHED; PG8_LDA(At, 1, 0); PG8_STAGE(PG8_SA(0, 1), a2 + hstep, voffA);
;             PG8_WAIT_V(8); PG8_WAIT_L(0); PG8_BAR; PG8_MMA(0, 0, At, B0); PG8_MMA(0, 1, At, B1); PG8_BAR; PG8_SCHED;
	v_mfma_f32_16x16x32_bf16 v[62:65], v[152:155], v[202:205], v[62:65]
	v_mfma_f32_16x16x32_bf16 v[58:61], v[164:167], v[202:205], v[58:61]
	v_mfma_f32_16x16x32_bf16 v[46:49], v[152:155], v[214:217], v[46:49]
	v_mfma_f32_16x16x32_bf16 v[42:45], v[164:167], v[214:217], v[42:45]
	v_mfma_f32_16x16x32_bf16 v[30:33], v[152:155], v[222:225], v[30:33]
	v_mfma_f32_16x16x32_bf16 v[26:29], v[164:167], v[222:225], v[26:29]
	v_mfma_f32_16x16x32_bf16 v[14:17], v[152:155], v[230:233], v[14:17]
	v_mfma_f32_16x16x32_bf16 v[10:13], v[164:167], v[230:233], v[10:13]
	v_mfma_f32_16x16x32_bf16 v[62:65], v[160:163], v[206:209], v[62:65]
	v_mfma_f32_16x16x32_bf16 v[58:61], v[182:185], v[206:209], v[58:61]
	v_mfma_f32_16x16x32_bf16 v[46:49], v[160:163], v[218:221], v[46:49]
	v_mfma_f32_16x16x32_bf16 v[42:45], v[182:185], v[218:221], v[42:45]
	v_mfma_f32_16x16x32_bf16 v[30:33], v[160:163], v[226:229], v[30:33]
	v_mfma_f32_16x16x32_bf16 v[26:29], v[182:185], v[226:229], v[26:29]
	v_mfma_f32_16x16x32_bf16 v[14:17], v[160:163], v[234:237], v[14:17]
	v_mfma_f32_16x16x32_bf16 v[10:13], v[182:185], v[234:237], v[10:13]
	s_setprio 0
	s_setprio 1
	v_mfma_f32_16x16x32_bf16 v[54:57], v[186:189], v[202:205], v[54:57]
	v_mfma_f32_16x16x32_bf16 v[50:53], v[194:197], v[202:205], v[50:53]
	v_mfma_f32_16x16x32_bf16 v[38:41], v[186:189], v[214:217], v[38:41]
	v_mfma_f32_16x16x32_bf16 v[34:37], v[194:197], v[214:217], v[34:37]
	v_mfma_f32_16x16x32_bf16 v[22:25], v[186:189], v[222:225], v[22:25]
	v_mfma_f32_16x16x32_bf16 v[18:21], v[194:197], v[222:225], v[18:21]
	v_mfma_f32_16x16x32_bf16 v[6:9], v[186:189], v[230:233], v[6:9]
	v_mfma_f32_16x16x32_bf16 v[2:5], v[194:197], v[230:233], v[2:5]
	v_mfma_f32_16x16x32_bf16 v[54:57], v[190:193], v[206:209], v[54:57]
	v_mfma_f32_16x16x32_bf16 v[50:53], v[198:201], v[206:209], v[50:53]
	v_mfma_f32_16x16x32_bf16 v[38:41], v[190:193], v[218:221], v[38:41]
	v_mfma_f32_16x16x32_bf16 v[34:37], v[198:201], v[218:221], v[34:37]
	v_mfma_f32_16x16x32_bf16 v[22:25], v[190:193], v[226:229], v[22:25]
	v_mfma_f32_16x16x32_bf16 v[18:21], v[198:201], v[226:229], v[18:21]
	v_mfma_f32_16x16x32_bf16 v[6:9], v[190:193], v[234:237], v[6:9]
	v_mfma_f32_16x16x32_bf16 v[2:5], v[198:201], v[234:237], v[2:5]
	s_setprio 0
	s_barrier
	s_add_i32 s86, 0, 0x18000
	v_add_u32_e32 v159, s86, v156
	s_add_i32 s87, 0, 0x1c000
	ds_read_b128 v[152:155], v159
	ds_read_b128 v[160:163], v159 offset:1024
	ds_read_b128 v[164:167], v159 offset:2048
	ds_read_b128 v[182:185], v159 offset:3072
	v_add_u32_e32 v159, s87, v156
	ds_read_b128 v[186:189], v159
	ds_read_b128 v[190:193], v159 offset:1024
	ds_read_b128 v[194:197], v159 offset:2048
	ds_read_b128 v[198:201], v159 offset:3072
	s_add_u32 s64, s64, 0x80000
	s_addc_u32 s65, s65, 0
	s_mov_b32 m0, s71
	v_lshl_add_u64 v[240:241], s[64:65], 0, v[134:135]
	ds_read_b128 v[202:205], v158 offset:32768
	ds_read_b128 v[206:209], v158 offset:33792
	ds_read_b128 v[214:217], v158 offset:34816
	ds_read_b128 v[218:221], v158 offset:35840
	ds_read_b128 v[222:225], v158 offset:36864
	ds_read_b128 v[226:229], v158 offset:37888
	ds_read_b128 v[230:233], v158 offset:38912
	ds_read_b128 v[234:237], v158 offset:39936
	global_load_lds_dwordx4 v[240:241], off
	v_lshl_add_u64 v[240:241], s[64:65], 0, v[132:133]
	s_mov_b32 m0, s72
	s_nop 0
	global_load_lds_dwordx4 v[240:241], off
	s_waitcnt vmcnt(8)
	s_waitcnt lgkmcnt(0)
	s_setprio 1
	s_barrier
	v_mfma_f32_16x16x32_bf16 v[126:129], v[152:155], v[202:205], v[126:129]
	v_mfma_f32_16x16x32_bf16 v[122:125], v[164:167], v[202:205], v[122:125]
	v_mfma_f32_16x16x32_bf16 v[110:113], v[152:155], v[214:217], v[110:113]
	v_mfma_f32_16x16x32_bf16 v[106:109], v[164:167], v[214:217], v[106:109]
	v_mfma_f32_16x16x32_bf16 v[94:97], v[152:155], v[222:225], v[94:97]
	v_mfma_f32_16x16x32_bf16 v[90:93], v[164:167], v[222:225], v[90:93]
	v_mfma_f32_16x16x32_bf16 v[78:81], v[152:155], v[230:233], v[78:81]
	v_mfma_f32_16x16x32_bf16 v[74:77], v[164:167], v[230:233], v[74:77]
	v_mfma_f32_16x16x32_bf16 v[126:129], v[160:163], v[206:209], v[126:129]
	v_mfma_f32_16x16x32_bf16 v[122:125], v[182:185], v[206:209], v[122:125]
	v_mfma_f32_16x16x32_bf16 v[110:113], v[160:163], v[218:221], v[110:113]
	v_mfma_f32_16x16x32_bf16 v[106:109], v[182:185], v[218:221], v[106:109]
	v_mfma_f32_16x16x32_bf16 v[94:97], v[160:163], v[226:229], v[94:97]
	v_mfma_f32_16x16x32_bf16 v[90:93], v[182:185], v[226:229], v[90:93]
	v_mfma_f32_16x16x32_bf16 v[78:81], v[160:163], v[234:237], v[78:81]
	v_mfma_f32_16x16x32_bf16 v[74:77], v[182:185], v[234:237], v[74:77]
	s_setprio 0
	s_setprio 1
	v_mfma_f32_16x16x32_bf16 v[118:121], v[186:189], v[202:205], v[118:121]
	v_mfma_f32_16x16x32_bf16 v[114:117], v[194:197], v[202:205], v[114:117]
	v_mfma_f32_16x16x32_bf16 v[102:105], v[186:189], v[214:217], v[102:105]
	v_mfma_f32_16x16x32_bf16 v[98:101], v[194:197], v[214:217], v[98:101]
	v_mfma_f32_16x16x32_bf16 v[86:89], v[186:189], v[222:225], v[86:89]
	v_mfma_f32_16x16x32_bf16 v[82:85], v[194:197], v[222:225], v[82:85]
	v_mfma_f32_16x16x32_bf16 v[70:73], v[186:189], v[230:233], v[70:73]
	v_mfma_f32_16x16x32_bf16 v[66:69], v[194:197], v[230:233], v[66:69]
	v_mfma_f32_16x16x32_bf16 v[118:121], v[190:193], v[206:209], v[118:121]
	v_mfma_f32_16x16x32_bf16 v[114:117], v[198:201], v[206:209], v[114:117]
	v_mfma_f32_16x16x32_bf16 v[102:105], v[190:193], v[218:221], v[102:105]
	v_mfma_f32_16x16x32_bf16 v[98:101], v[198:201], v[218:221], v[98:101]
	v_mfma_f32_16x16x32_bf16 v[86:89], v[190:193], v[226:229], v[86:89]
	v_mfma_f32_16x16x32_bf16 v[82:85], v[198:201], v[226:229], v[82:85]
	v_mfma_f32_16x16x32_bf16 v[70:73], v[190:193], v[234:237], v[70:73]
	v_mfma_f32_16x16x32_bf16 v[66:69], v[198:201], v[234:237], v[66:69]
	s_setprio 0
	s_barrier
; #define PG8_STAGE(bufoff, gbase, voff) do { _Pragma("unroll") for (int _i = 0; _i < 2; ++_i) \
;         __builtin_amdgcn_global_load_lds((const unsigned*)((const char*)(gbase) + (voff)[_i]), (PG8_LAS unsigned*)(lds + (bufoff) + ldsw + _i * 8192), 16, 0, 0); } while (0)
; #define PG8_LDA(dst, b, h) do { _Pragma("unroll") for (int m = 0; m < 4; ++m) _Pragma("unroll") for (int k = 0; k < 2; ++k) dst[m][k] = *(const PG8_LAS bf16x8*)(lds + PG8_SA(b, h) + aoff + m * 2048 + k * 1024); } while (0)
; #define PG8_MMA(ai, bj, At, Bt) do { __builtin_amdgcn_s_setprio(1); _Pragma("unroll") for (int m = 0; m < 4; ++m) _Pragma("unroll") for (int n = 0; n < 2; ++n) _Pragma("unroll") for (int k = 0; k < 2; ++k) \
;         acc[ai][bj][m][n] = __builtin_amdgcn_mfma_f32_16x16x32_bf16(Bt[n][k], At[m][k], acc[ai][bj][m][n], 0, 0, 0); __builtin_amdgcn_s_setprio(0); } while (0)
; #define PG8_WAIT_V(n) asm volatile("s_waitcnt vmcnt(" #n ")" ::: "memory")
; #define PG8_WAIT_L(n) asm volatile("s_waitcnt lgkmcnt(" #n ")" ::: "memory")
; #define PG8_BAR __builtin_amdgcn_s_barrier()
; #define PG8_SCHED __builtin_amdgcn_sched_barrier(0)
; template <class Epi, class Sched, bool ALIGN_EPI = false, bool SP2 = false>
; __device__ __forceinline__ void gemm_phase(PG8_LAS unsigned char* lds, const Gemm g, const Sched& S, const Epi& E) {
;     ...
;         for (int t = 0; t < nt; t += 2) {
;             const bool last = (t == nt - 2);
;     ...
;             PG8_LDA(At, 1, 1); PG8_STAGE(PG8_SB(1, 0), b3, voffB); PG8_STAGE(PG8_SB(1, 1), b3 + hstep, voffB); PG8_STAGE(PG8_SA(1, 0), a3, voffA);
;             PG8_WAIT_V(8); PG8_WAIT_L(0); PG8_BAR; PG8_MMA(1, 0, At, B0); PG8_MMA(1, 1, At, B1); PG8_BAR; PG8_SCHED;
	s_add_i32 s64, s86, s68
	v_lshl_add_u64 v[142:143], v[142:143], 0, s[34:35]
	s_mov_b32 m0, s64
	ds_read_b128 v[202:205], v158 offset:49152
	ds_read_b128 v[206:209], v158 offset:50176
	ds_read_b128 v[214:217], v158 offset:51200
	ds_read_b128 v[218:221], v158 offset:52224
	ds_read_b128 v[222:225], v158 offset:53248
	ds_read_b128 v[226:229], v158 offset:54272
	ds_read_b128 v[230:233], v158 offset:55296
	ds_read_b128 v[234:237], v158 offset:56320
	global_load_lds_dwordx4 v[142:143], off
	s_add_i32 m0, s64, 0x2000
	s_add_u32 s62, s62, 0x80080
	v_lshl_add_u64 v[142:143], v[144:145], 0, s[34:35]
	s_addc_u32 s63, s63, 0
	s_add_i32 s64, s87, s68
	global_load_lds_dwordx4 v[142:143], off
	v_lshl_add_u64 v[142:143], s[62:63], 0, v[0:1]
	s_mov_b32 m0, s64
	s_nop 0
	global_load_lds_dwordx4 v[142:143], off
	v_lshl_add_u64 v[142:143], s[62:63], 0, v[130:131]
	s_add_i32 m0, s64, 0x2000
	s_nop 0
	global_load_lds_dwordx4 v[142:143], off
	v_lshl_add_u64 v[142:143], v[168:169], 0, s[34:35]
	s_mov_b32 m0, s74
	s_nop 0
	global_load_lds_dwordx4 v[142:143], off
	v_lshl_add_u64 v[142:143], v[238:239], 0, s[34:35]
	s_mov_b32 m0, s75
	s_nop 0
	global_load_lds_dwordx4 v[142:143], off
	s_waitcnt vmcnt(8)
	s_waitcnt lgkmcnt(0)
	s_setprio 1
	s_barrier
	v_mfma_f32_16x16x32_bf16 v[62:65], v[152:155], v[202:205], v[62:65]
	v_mfma_f32_16x16x32_bf16 v[58:61], v[164:167], v[202:205], v[58:61]
	v_mfma_f32_16x16x32_bf16 v[46:49], v[152:155], v[214:217], v[46:49]
	v_mfma_f32_16x16x32_bf16 v[42:45], v[164:167], v[214:217], v[42:45]
	v_mfma_f32_16x16x32_bf16 v[30:33], v[152:155], v[222:225], v[30:33]
	v_mfma_f32_16x16x32_bf16 v[26:29], v[164:167], v[222:225], v[26:29]
	v_mfma_f32_16x16x32_bf16 v[14:17], v[152:155], v[230:233], v[14:17]
	v_mfma_f32_16x16x32_bf16 v[10:13], v[164:167], v[230:233], v[10:13]
	v_mfma_f32_16x16x32_bf16 v[62:65], v[160:163], v[206:209], v[62:65]
	v_mfma_f32_16x16x32_bf16 v[58:61], v[182:185], v[206:209], v[58:61]
	v_mfma_f32_16x16x32_bf16 v[46:49], v[160:163], v[218:221], v[46:49]
	v_mfma_f32_16x16x32_bf16 v[42:45], v[182:185], v[218:221], v[42:45]
	v_mfma_f32_16x16x32_bf16 v[30:33], v[160:163], v[226:229], v[30:33]
	v_mfma_f32_16x16x32_bf16 v[26:29], v[182:185], v[226:229], v[26:29]
	v_mfma_f32_16x16x32_bf16 v[14:17], v[160:163], v[234:237], v[14:17]
	v_mfma_f32_16x16x32_bf16 v[10:13], v[182:185], v[234:237], v[10:13]
	s_setprio 0
	s_setprio 1
	v_mfma_f32_16x16x32_bf16 v[54:57], v[186:189], v[202:205], v[54:57]
	v_mfma_f32_16x16x32_bf16 v[50:53], v[194:197], v[202:205], v[50:53]
	v_mfma_f32_16x16x32_bf16 v[38:41], v[186:189], v[214:217], v[38:41]
	v_mfma_f32_16x16x32_bf16 v[34:37], v[194:197], v[214:217], v[34:37]
	v_mfma_f32_16x16x32_bf16 v[22:25], v[186:189], v[222:225], v[22:25]
	v_mfma_f32_16x16x32_bf16 v[18:21], v[194:197], v[222:225], v[18:21]
	v_mfma_f32_16x16x32_bf16 v[6:9], v[186:189], v[230:233], v[6:9]
	v_mfma_f32_16x16x32_bf16 v[2:5], v[194:197], v[230:233], v[2:5]
	v_mfma_f32_16x16x32_bf16 v[54:57], v[190:193], v[206:209], v[54:57]
	v_mfma_f32_16x16x32_bf16 v[50:53], v[198:201], v[206:209], v[50:53]
	v_mfma_f32_16x16x32_bf16 v[38:41], v[190:193], v[218:221], v[38:41]
	v_mfma_f32_16x16x32_bf16 v[34:37], v[198:201], v[218:221], v[34:37]
	v_mfma_f32_16x16x32_bf16 v[22:25], v[190:193], v[226:229], v[22:25]
	v_mfma_f32_16x16x32_bf16 v[18:21], v[198:201], v[226:229], v[18:21]
	v_mfma_f32_16x16x32_bf16 v[6:9], v[190:193], v[234:237], v[6:9]
	v_mfma_f32_16x16x32_bf16 v[2:5], v[198:201], v[234:237], v[2:5]
	s_add_i32 s83, s83, 2
	s_add_u32 s79, s79, 0x100
	s_addc_u32 s82, s82, 0
	s_add_u32 s60, s60, 0x100
	s_addc_u32 s61, s61, 0
	s_cmp_gt_u32 s83, 29
	s_setprio 0
	s_cbranch_scc0 .Lg3_head_bar
	s_barrier
	s_and_b64 vcc, exec, s[50:51]
	s_cbranch_vccz .LBB0_41
	s_barrier

; #define PG8_STAGE(bufoff, gbase, voff) do { _Pragma("unroll") for (int _i = 0; _i < 2; ++_i) \
;         __builtin_amdgcn_global_load_lds((const unsigned*)((const char*)(gbase) + (voff)[_i]), (PG8_LAS unsigned*)(lds + (bufoff) + ldsw + _i * 8192), 16, 0, 0); } while (0)
; #define PG8_LDA(dst, b, h) do { _Pragma("unroll") for (int m = 0; m < 4; ++m) _Pragma("unroll") for (int k = 0; k < 2; ++k) dst[m][k] = *(const PG8_LAS bf16x8*)(lds + PG8_SA(b, h) + aoff + m * 2048 + k * 1024); } while (0)
; #define PG8_LDB(dst, b, h) do { _Pragma("unroll") for (int n = 0; n < 2; ++n) _Pragma("unroll") for (int k = 0; k < 2; ++k) dst[n][k] = *(const PG8_LAS bf16x8*)(lds + PG8_SB(b, h) + boff + n * 2048 + k * 1024); } while (0)
; #define PG8_MMA(ai, bj, At, Bt) do { __builtin_amdgcn_s_setprio(1); _Pragma("unroll") for (int m = 0; m < 4; ++m) _Pragma("unroll") for (int n = 0; n < 2; ++n) _Pragma("unroll") for (int k = 0; k < 2; ++k) \
;         acc[ai][bj][m][n] = __builtin_amdgcn_mfma_f32_16x16x32_bf16(Bt[n][k], At[m][k], acc[ai][bj][m][n], 0, 0, 0); __builtin_amdgcn_s_setprio(0); } while (0)
; #define PG8_WAIT_V(n) asm volatile("s_waitcnt vmcnt(" #n ")" ::: "memory")
; template <class Epi, class Sched, bool ALIGN_EPI = false, bool SP2 = false>
; __device__ __forceinline__ void gemm_phase(PG8_LAS unsigned char* lds, const Gemm g, const Sched& S, const Epi& E) {
;     ...
;             const bool last = (t == nt - 2);
;             const char* a1 = cA + (size_t)(t + 1) * kstep;
;             const char* a2 = last ? nA : cA + (size_t)(t + 2) * kstep; const char* b2 = last ? nB : cB + (size_t)(t + 2) * kstep;
;             const char* a3 = a2 + kstep; const char* b3 = b2 + kstep;
;             if (last && has_next) S.a_ready(nxt);
;             if constexpr (Epi::MID) { if (t == nt / 2) E.mid(acc, cur, wr, wc, fr, fq); }
;             if constexpr (SP2) {
;             PG8_LDB(B0, 0, 0); PG8_LDB(B1, 0, 1); PG8_SCHED; PG8_LDA(At, 0, 0); PG8_STAGE(PG8_SA(1, 1), a1 + hstep, voffA);
;             PG8_WAIT_V(8); PG8_WAIT_L(0); PG8_BAR; PG8_MMA(0, 0, At, B0); PG8_MMA(0, 1, At, B1); PG8_BAR; PG8_SCHED;
;             PG8_LDA(At, 0, 1); PG8_STAGE(PG8_SB(0, 0), b2, voffB); PG8_STAGE(PG8_SB(0, 1), b2 + hstep, voffB); PG8_STAGE(PG8_SA(0, 0), a2, voffA);
;             PG8_WAIT_V(8); PG8_WAIT_L(0); PG8_BAR; PG8_MMA(1, 0, At, B0); PG8_MMA(1, 1, At, B1); PG8_BAR; PG8_SCHED;
.LBB0_418:
	s_add_u32 s56, s40, 0xfff80080
	s_addc_u32 s57, s41, -1
	s_add_i32 s75, 0, 0x10000
	s_cmp_eq_u32 s74, 28
	s_cselect_b32 s59, s2, s57
	s_cselect_b32 s58, s3, s56
	v_add_u32_e32 v142, s75, v156
	s_cselect_b32 s57, s49, s73
	s_cselect_b32 s56, s51, s72
	s_add_i32 s78, 0, 0x14000
	ds_read_b128 v[152:155], v142
	ds_read_b128 v[160:163], v142 offset:1024
	ds_read_b128 v[164:167], v142 offset:2048
	ds_read_b128 v[182:185], v142 offset:3072
	v_add_u32_e32 v142, s78, v156
	ds_read_b128 v[186:189], v142
	ds_read_b128 v[190:193], v142 offset:1024
	ds_read_b128 v[194:197], v142 offset:2048
	ds_read_b128 v[198:201], v142 offset:3072
	v_lshl_add_u64 v[168:169], s[40:41], 0, v[150:151]
	s_add_i32 m0, s63, 0xc000
	ds_read_b128 v[202:205], v158
	ds_read_b128 v[206:209], v158 offset:1024
	ds_read_b128 v[214:217], v158 offset:2048
	ds_read_b128 v[218:221], v158 offset:3072
	ds_read_b128 v[222:225], v158 offset:4096
	ds_read_b128 v[226:229], v158 offset:5120
	ds_read_b128 v[230:233], v158 offset:6144
	ds_read_b128 v[234:237], v158 offset:7168
	global_load_lds_dwordx4 v[168:169], off
	v_lshl_add_u64 v[168:169], s[40:41], 0, v[136:137]
	s_add_i32 m0, s63, 0xe000
	s_nop 0
	global_load_lds_dwordx4 v[168:169], off
	s_waitcnt vmcnt(8)
	s_waitcnt lgkmcnt(0)
	s_setprio 1
	s_barrier
	v_mfma_f32_16x16x32_bf16 v[126:129], v[152:155], v[202:205], v[126:129]
	v_mfma_f32_16x16x32_bf16 v[122:125], v[164:167], v[202:205], v[122:125]
	v_mfma_f32_16x16x32_bf16 v[110:113], v[152:155], v[214:217], v[110:113]
	v_mfma_f32_16x16x32_bf16 v[106:109], v[164:167], v[214:217], v[106:109]
	v_mfma_f32_16x16x32_bf16 v[94:97], v[152:155], v[222:225], v[94:97]
	v_mfma_f32_16x16x32_bf16 v[90:93], v[164:167], v[222:225], v[90:93]
	v_mfma_f32_16x16x32_bf16 v[78:81], v[152:155], v[230:233], v[78:81]
	v_mfma_f32_16x16x32_bf16 v[74:77], v[164:167], v[230:233], v[74:77]
	v_mfma_f32_16x16x32_bf16 v[126:129], v[160:163], v[206:209], v[126:129]
	v_mfma_f32_16x16x32_bf16 v[122:125], v[182:185], v[206:209], v[122:125]
	v_mfma_f32_16x16x32_bf16 v[110:113], v[160:163], v[218:221], v[110:113]
	v_mfma_f32_16x16x32_bf16 v[106:109], v[182:185], v[218:221], v[106:109]
	v_mfma_f32_16x16x32_bf16 v[94:97], v[160:163], v[226:229], v[94:97]
	v_mfma_f32_16x16x32_bf16 v[90:93], v[182:185], v[226:229], v[90:93]
	v_mfma_f32_16x16x32_bf16 v[78:81], v[160:163], v[234:237], v[78:81]
	v_mfma_f32_16x16x32_bf16 v[74:77], v[182:185], v[234:237], v[74:77]
	s_setprio 0
	s_setprio 1
	v_mfma_f32_16x16x32_bf16 v[118:121], v[186:189], v[202:205], v[118:121]
	v_mfma_f32_16x16x32_bf16 v[114:117], v[194:197], v[202:205], v[114:117]
	v_mfma_f32_16x16x32_bf16 v[102:105], v[186:189], v[214:217], v[102:105]
	v_mfma_f32_16x16x32_bf16 v[98:101], v[194:197], v[214:217], v[98:101]
	v_mfma_f32_16x16x32_bf16 v[86:89], v[186:189], v[222:225], v[86:89]
	v_mfma_f32_16x16x32_bf16 v[82:85], v[194:197], v[222:225], v[82:85]
	v_mfma_f32_16x16x32_bf16 v[70:73], v[186:189], v[230:233], v[70:73]
	v_mfma_f32_16x16x32_bf16 v[66:69], v[194:197], v[230:233], v[66:69]
	v_mfma_f32_16x16x32_bf16 v[118:121], v[190:193], v[206:209], v[118:121]
	v_mfma_f32_16x16x32_bf16 v[114:117], v[198:201], v[206:209], v[114:117]
	v_mfma_f32_16x16x32_bf16 v[102:105], v[190:193], v[218:221], v[102:105]
	v_mfma_f32_16x16x32_bf16 v[98:101], v[198:201], v[218:221], v[98:101]
	v_mfma_f32_16x16x32_bf16 v[86:89], v[190:193], v[226:229], v[86:89]
	v_mfma_f32_16x16x32_bf16 v[82:85], v[198:201], v[226:229], v[82:85]
	v_mfma_f32_16x16x32_bf16 v[70:73], v[190:193], v[234:237], v[70:73]
	v_mfma_f32_16x16x32_bf16 v[66:69], v[198:201], v[234:237], v[66:69]
	s_setprio 0
	s_barrier
	s_add_i32 s75, s75, s62
	v_lshl_add_u64 v[168:169], s[56:57], 0, v[0:1]
	s_mov_b32 m0, s75
	ds_read_b128 v[202:205], v158 offset:16384
	ds_read_b128 v[206:209], v158 offset:17408
	ds_read_b128 v[214:217], v158 offset:18432
	ds_read_b128 v[218:221], v158 offset:19456
	ds_read_b128 v[222:225], v158 offset:20480
	ds_read_b128 v[226:229], v158 offset:21504
	ds_read_b128 v[230:233], v158 offset:22528
	ds_read_b128 v[234:237], v158 offset:23552
	global_load_lds_dwordx4 v[168:169], off
	s_add_i32 m0, s75, 0x2000
	s_add_u32 s76, s56, 0x80000
	v_lshl_add_u64 v[238:239], s[56:57], 0, v[130:131]
	s_addc_u32 s77, s57, 0
	s_add_i32 s75, s78, s62
	global_load_lds_dwordx4 v[238:239], off
	v_lshl_add_u64 v[240:241], s[76:77], 0, v[0:1]
	s_mov_b32 m0, s75
	v_lshl_add_u64 v[242:243], s[58:59], 0, v[132:133]
	global_load_lds_dwordx4 v[240:241], off
	v_lshl_add_u64 v[240:241], s[76:77], 0, v[130:131]
	s_add_i32 m0, s75, 0x2000
	s_nop 0
	global_load_lds_dwordx4 v[240:241], off
	v_lshl_add_u64 v[240:241], s[58:59], 0, v[134:135]
	s_mov_b32 m0, s63
	s_nop 0
	global_load_lds_dwordx4 v[240:241], off
	s_mov_b32 m0, s64
	s_nop 0
	global_load_lds_dwordx4 v[242:243], off
	s_waitcnt vmcnt(8)
	s_waitcnt lgkmcnt(0)
	s_setprio 1
	s_barrier
; #define PG8_STAGE(bufoff, gbase, voff) do { _Pragma("unroll") for (int _i = 0; _i < 2; ++_i) \
;         __builtin_amdgcn_global_load_lds((const unsigned*)((const char*)(gbase) + (voff)[_i]), (PG8_LAS unsigned*)(lds + (bufoff) + ldsw + _i * 8192), 16, 0, 0); } while (0)
; #define PG8_LDA(dst, b, h) do { _Pragma("unroll") for (int m = 0; m < 4; ++m) _Pragma("unroll") for (int k = 0; k < 2; ++k) dst[m][k] = *(const PG8_LAS bf16x8*)(lds + PG8_SA(b, h) + aoff + m * 2048 + k * 1024); } while (0)
; #define PG8_LDB(dst, b, h) do { _Pragma("unroll") for (int n = 0; n < 2; ++n) _Pragma("unroll") for (int k = 0; k < 2; ++k) dst[n][k] = *(const PG8_LAS bf16x8*)(lds + PG8_SB(b, h) + boff + n * 2048 + k * 1024); } while (0)
; #define PG8_MMA(ai, bj, At, Bt) do { __builtin_amdgcn_s_setprio(1); _Pragma("unroll") for (int m = 0; m < 4; ++m) _Pragma("unroll") for (int n = 0; n < 2; ++n) _Pragma("unroll") for (int k = 0; k < 2; ++k) \
;         acc[ai][bj][m][n] = __builtin_amdgcn_mfma_f32_16x16x32_bf16(Bt[n][k], At[m][k], acc[ai][bj][m][n], 0, 0, 0); __builtin_amdgcn_s_setprio(0); } while (0)
; #define PG8_WAIT_V(n) asm volatile("s_waitcnt vmcnt(" #n ")" ::: "memory")
; #define PG8_WAIT_L(n) asm volatile("s_waitcnt lgkmcnt(" #n ")" ::: "memory")
; #define PG8_BAR __builtin_amdgcn_s_barrier()
; #define PG8_SCHED __builtin_amdgcn_sched_barrier(0)
; template <class Epi, class Sched, bool ALIGN_EPI = false, bool SP2 = false>
; __device__ __forceinline__ void gemm_phase(PG8_LAS unsigned char* lds, const Gemm g, const Sched& S, const Epi& E) {
;     ...
;             PG8_WAIT_V(8); PG8_WAIT_L(0); PG8_BAR; PG8_MMA(1, 0, At, B0); PG8_MMA(1, 1, At, B1); PG8_BAR; PG8_SCHED;
;             PG8_LDB(B0, 1, 0); PG8_LDB(B1, 1, 1); PG8_SCHED; PG8_LDA(At, 1, 0); PG8_STAGE(PG8_SA(0, 1), a2 + hstep, voffA);
;             PG8_WAIT_V(8); PG8_WAIT_L(0); PG8_BAR; PG8_MMA(0, 0, At, B0); PG8_MMA(0, 1, At, B1); PG8_BAR; PG8_SCHED;
	v_mfma_f32_16x16x32_bf16 v[62:65], v[152:155], v[202:205], v[62:65]
	v_mfma_f32_16x16x32_bf16 v[58:61], v[164:167], v[202:205], v[58:61]
	v_mfma_f32_16x16x32_bf16 v[46:49], v[152:155], v[214:217], v[46:49]
	v_mfma_f32_16x16x32_bf16 v[42:45], v[164:167], v[214:217], v[42:45]
	v_mfma_f32_16x16x32_bf16 v[30:33], v[152:155], v[222:225], v[30:33]
	v_mfma_f32_16x16x32_bf16 v[26:29], v[164:167], v[222:225], v[26:29]
	v_mfma_f32_16x16x32_bf16 v[14:17], v[152:155], v[230:233], v[14:17]
	v_mfma_f32_16x16x32_bf16 v[10:13], v[164:167], v[230:233], v[10:13]
	v_mfma_f32_16x16x32_bf16 v[62:65], v[160:163], v[206:209], v[62:65]
	v_mfma_f32_16x16x32_bf16 v[58:61], v[182:185], v[206:209], v[58:61]
	v_mfma_f32_16x16x32_bf16 v[46:49], v[160:163], v[218:221], v[46:49]
	v_mfma_f32_16x16x32_bf16 v[42:45], v[182:185], v[218:221], v[42:45]
	v_mfma_f32_16x16x32_bf16 v[30:33], v[160:163], v[226:229], v[30:33]
	v_mfma_f32_16x16x32_bf16 v[26:29], v[182:185], v[226:229], v[26:29]
	v_mfma_f32_16x16x32_bf16 v[14:17], v[160:163], v[234:237], v[14:17]
	v_mfma_f32_16x16x32_bf16 v[10:13], v[182:185], v[234:237], v[10:13]
	s_setprio 0
	s_setprio 1
	v_mfma_f32_16x16x32_bf16 v[54:57], v[186:189], v[202:205], v[54:57]
	v_mfma_f32_16x16x32_bf16 v[50:53], v[194:197], v[202:205], v[50:53]
	v_mfma_f32_16x16x32_bf16 v[38:41], v[186:189], v[214:217], v[38:41]
	v_mfma_f32_16x16x32_bf16 v[34:37], v[194:197], v[214:217], v[34:37]
	v_mfma_f32_16x16x32_bf16 v[22:25], v[186:189], v[222:225], v[22:25]
	v_mfma_f32_16x16x32_bf16 v[18:21], v[194:197], v[222:225], v[18:21]
	v_mfma_f32_16x16x32_bf16 v[6:9], v[186:189], v[230:233], v[6:9]
	v_mfma_f32_16x16x32_bf16 v[2:5], v[194:197], v[230:233], v[2:5]
	v_mfma_f32_16x16x32_bf16 v[54:57], v[190:193], v[206:209], v[54:57]
	v_mfma_f32_16x16x32_bf16 v[50:53], v[198:201], v[206:209], v[50:53]
	v_mfma_f32_16x16x32_bf16 v[38:41], v[190:193], v[218:221], v[38:41]
	v_mfma_f32_16x16x32_bf16 v[34:37], v[198:201], v[218:221], v[34:37]
	v_mfma_f32_16x16x32_bf16 v[22:25], v[190:193], v[226:229], v[22:25]
	v_mfma_f32_16x16x32_bf16 v[18:21], v[198:201], v[226:229], v[18:21]
	v_mfma_f32_16x16x32_bf16 v[6:9], v[190:193], v[234:237], v[6:9]
	v_mfma_f32_16x16x32_bf16 v[2:5], v[198:201], v[234:237], v[2:5]
	s_setprio 0
	s_barrier
	s_add_i32 s75, 0, 0x18000
	v_add_u32_e32 v142, s75, v156
	s_add_i32 s76, 0, 0x1c000
	ds_read_b128 v[152:155], v142
	ds_read_b128 v[160:163], v142 offset:1024
	ds_read_b128 v[164:167], v142 offset:2048
	ds_read_b128 v[182:185], v142 offset:3072
	v_add_u32_e32 v142, s76, v156
	ds_read_b128 v[186:189], v142
	ds_read_b128 v[190:193], v142 offset:1024
	ds_read_b128 v[194:197], v142 offset:2048
	ds_read_b128 v[198:201], v142 offset:3072
	s_add_u32 s58, s58, 0x80000
	s_addc_u32 s59, s59, 0
	s_mov_b32 m0, s65
	v_lshl_add_u64 v[244:245], s[58:59], 0, v[134:135]
	ds_read_b128 v[202:205], v158 offset:32768
	ds_read_b128 v[206:209], v158 offset:33792
	ds_read_b128 v[214:217], v158 offset:34816
	ds_read_b128 v[218:221], v158 offset:35840
	ds_read_b128 v[222:225], v158 offset:36864
	ds_read_b128 v[226:229], v158 offset:37888
	ds_read_b128 v[230:233], v158 offset:38912
	ds_read_b128 v[234:237], v158 offset:39936
	global_load_lds_dwordx4 v[244:245], off
	v_lshl_add_u64 v[244:245], s[58:59], 0, v[132:133]
	s_mov_b32 m0, s66
	s_nop 0
	global_load_lds_dwordx4 v[244:245], off
	s_waitcnt vmcnt(8)
	s_waitcnt lgkmcnt(0)
	s_setprio 1
	s_barrier
	v_mfma_f32_16x16x32_bf16 v[126:129], v[152:155], v[202:205], v[126:129]
	v_mfma_f32_16x16x32_bf16 v[122:125], v[164:167], v[202:205], v[122:125]
	v_mfma_f32_16x16x32_bf16 v[110:113], v[152:155], v[214:217], v[110:113]
	v_mfma_f32_16x16x32_bf16 v[106:109], v[164:167], v[214:217], v[106:109]
	v_mfma_f32_16x16x32_bf16 v[94:97], v[152:155], v[222:225], v[94:97]
	v_mfma_f32_16x16x32_bf16 v[90:93], v[164:167], v[222:225], v[90:93]
	v_mfma_f32_16x16x32_bf16 v[78:81], v[152:155], v[230:233], v[78:81]
	v_mfma_f32_16x16x32_bf16 v[74:77], v[164:167], v[230:233], v[74:77]
	v_mfma_f32_16x16x32_bf16 v[126:129], v[160:163], v[206:209], v[126:129]
	v_mfma_f32_16x16x32_bf16 v[122:125], v[182:185], v[206:209], v[122:125]
	v_mfma_f32_16x16x32_bf16 v[110:113], v[160:163], v[218:221], v[110:113]
	v_mfma_f32_16x16x32_bf16 v[106:109], v[182:185], v[218:221], v[106:109]
	v_mfma_f32_16x16x32_bf16 v[94:97], v[160:163], v[226:229], v[94:97]
	v_mfma_f32_16x16x32_bf16 v[90:93], v[182:185], v[226:229], v[90:93]
	v_mfma_f32_16x16x32_bf16 v[78:81], v[160:163], v[234:237], v[78:81]
	v_mfma_f32_16x16x32_bf16 v[74:77], v[182:185], v[234:237], v[74:77]
	s_setprio 0
	s_setprio 1
	v_mfma_f32_16x16x32_bf16 v[118:121], v[186:189], v[202:205], v[118:121]
	v_mfma_f32_16x16x32_bf16 v[114:117], v[194:197], v[202:205], v[114:117]
	v_mfma_f32_16x16x32_bf16 v[102:105], v[186:189], v[214:217], v[102:105]
	v_mfma_f32_16x16x32_bf16 v[98:101], v[194:197], v[214:217], v[98:101]
	v_mfma_f32_16x16x32_bf16 v[86:89], v[186:189], v[222:225], v[86:89]
	v_mfma_f32_16x16x32_bf16 v[82:85], v[194:197], v[222:225], v[82:85]
	v_mfma_f32_16x16x32_bf16 v[70:73], v[186:189], v[230:233], v[70:73]
	v_mfma_f32_16x16x32_bf16 v[66:69], v[194:197], v[230:233], v[66:69]
	v_mfma_f32_16x16x32_bf16 v[118:121], v[190:193], v[206:209], v[118:121]
	v_mfma_f32_16x16x32_bf16 v[114:117], v[198:201], v[206:209], v[114:117]
	v_mfma_f32_16x16x32_bf16 v[102:105], v[190:193], v[218:221], v[102:105]
	v_mfma_f32_16x16x32_bf16 v[98:101], v[198:201], v[218:221], v[98:101]
	v_mfma_f32_16x16x32_bf16 v[86:89], v[190:193], v[226:229], v[86:89]
	v_mfma_f32_16x16x32_bf16 v[82:85], v[198:201], v[226:229], v[82:85]
	v_mfma_f32_16x16x32_bf16 v[70:73], v[190:193], v[234:237], v[70:73]
	v_mfma_f32_16x16x32_bf16 v[66:69], v[198:201], v[234:237], v[66:69]
	s_setprio 0
	s_barrier
; #define PG8_STAGE(bufoff, gbase, voff) do { _Pragma("unroll") for (int _i = 0; _i < 2; ++_i) \
;         __builtin_amdgcn_global_load_lds((const unsigned*)((const char*)(gbase) + (voff)[_i]), (PG8_LAS unsigned*)(lds + (bufoff) + ldsw + _i * 8192), 16, 0, 0); } while (0)
; #define PG8_LDA(dst, b, h) do { _Pragma("unroll") for (int m = 0; m < 4; ++m) _Pragma("unroll") for (int k = 0; k < 2; ++k) dst[m][k] = *(const PG8_LAS bf16x8*)(lds + PG8_SA(b, h) + aoff + m * 2048 + k * 1024); } while (0)
; #define PG8_MMA(ai, bj, At, Bt) do { __builtin_amdgcn_s_setprio(1); _Pragma("unroll") for (int m = 0; m < 4; ++m) _Pragma("unroll") for (int n = 0; n < 2; ++n) _Pragma("unroll") for (int k = 0; k < 2; ++k) \
;         acc[ai][bj][m][n] = __builtin_amdgcn_mfma_f32_16x16x32_bf16(Bt[n][k], At[m][k], acc[ai][bj][m][n], 0, 0, 0); __builtin_amdgcn_s_setprio(0); } while (0)
; #define PG8_WAIT_V(n) asm volatile("s_waitcnt vmcnt(" #n ")" ::: "memory")
; #define PG8_WAIT_L(n) asm volatile("s_waitcnt lgkmcnt(" #n ")" ::: "memory")
; #define PG8_BAR __builtin_amdgcn_s_barrier()
; #define PG8_SCHED __builtin_amdgcn_sched_barrier(0)
; template <class Epi, class Sched, bool ALIGN_EPI = false, bool SP2 = false>
; __device__ __forceinline__ void gemm_phase(PG8_LAS unsigned char* lds, const Gemm g, const Sched& S, const Epi& E) {
;     ...
;         for (int t = 0; t < nt; t += 2) {
;             const bool last = (t == nt - 2);
;     ...
;             PG8_LDA(At, 1, 1); PG8_STAGE(PG8_SB(1, 0), b3, voffB); PG8_STAGE(PG8_SB(1, 1), b3 + hstep, voffB); PG8_STAGE(PG8_SA(1, 0), a3, voffA);
;             PG8_WAIT_V(8); PG8_WAIT_L(0); PG8_BAR; PG8_MMA(1, 0, At, B0); PG8_MMA(1, 1, At, B1); PG8_BAR; PG8_SCHED;
	s_add_i32 s58, s75, s62
	v_lshl_add_u64 v[168:169], v[168:169], 0, s[34:35]
	s_mov_b32 m0, s58
	ds_read_b128 v[202:205], v158 offset:49152
	ds_read_b128 v[206:209], v158 offset:50176
	ds_read_b128 v[214:217], v158 offset:51200
	ds_read_b128 v[218:221], v158 offset:52224
	ds_read_b128 v[222:225], v158 offset:53248
	ds_read_b128 v[226:229], v158 offset:54272
	ds_read_b128 v[230:233], v158 offset:55296
	ds_read_b128 v[234:237], v158 offset:56320
	global_load_lds_dwordx4 v[168:169], off
	s_add_i32 m0, s58, 0x2000
	s_add_u32 s56, s56, 0x80080
	v_lshl_add_u64 v[168:169], v[238:239], 0, s[34:35]
	s_addc_u32 s57, s57, 0
	s_add_i32 s58, s76, s62
	global_load_lds_dwordx4 v[168:169], off
	v_lshl_add_u64 v[168:169], s[56:57], 0, v[0:1]
	s_mov_b32 m0, s58
	s_nop 0
	global_load_lds_dwordx4 v[168:169], off
	v_lshl_add_u64 v[168:169], s[56:57], 0, v[130:131]
	s_add_i32 m0, s58, 0x2000
	s_nop 0
	global_load_lds_dwordx4 v[168:169], off
	v_lshl_add_u64 v[168:169], v[240:241], 0, s[34:35]
	s_mov_b32 m0, s67
	s_nop 0
	global_load_lds_dwordx4 v[168:169], off
	v_lshl_add_u64 v[168:169], v[242:243], 0, s[34:35]
	s_mov_b32 m0, s68
	s_nop 0
	global_load_lds_dwordx4 v[168:169], off
	s_waitcnt vmcnt(8)
	s_waitcnt lgkmcnt(0)
	s_setprio 1
	s_barrier
	v_mfma_f32_16x16x32_bf16 v[62:65], v[152:155], v[202:205], v[62:65]
	v_mfma_f32_16x16x32_bf16 v[58:61], v[164:167], v[202:205], v[58:61]
	v_mfma_f32_16x16x32_bf16 v[46:49], v[152:155], v[214:217], v[46:49]
	v_mfma_f32_16x16x32_bf16 v[42:45], v[164:167], v[214:217], v[42:45]
	v_mfma_f32_16x16x32_bf16 v[30:33], v[152:155], v[222:225], v[30:33]
	v_mfma_f32_16x16x32_bf16 v[26:29], v[164:167], v[222:225], v[26:29]
	v_mfma_f32_16x16x32_bf16 v[14:17], v[152:155], v[230:233], v[14:17]
	v_mfma_f32_16x16x32_bf16 v[10:13], v[164:167], v[230:233], v[10:13]
	v_mfma_f32_16x16x32_bf16 v[62:65], v[160:163], v[206:209], v[62:65]
	v_mfma_f32_16x16x32_bf16 v[58:61], v[182:185], v[206:209], v[58:61]
	v_mfma_f32_16x16x32_bf16 v[46:49], v[160:163], v[218:221], v[46:49]
	v_mfma_f32_16x16x32_bf16 v[42:45], v[182:185], v[218:221], v[42:45]
	v_mfma_f32_16x16x32_bf16 v[30:33], v[160:163], v[226:229], v[30:33]
	v_mfma_f32_16x16x32_bf16 v[26:29], v[182:185], v[226:229], v[26:29]
	v_mfma_f32_16x16x32_bf16 v[14:17], v[160:163], v[234:237], v[14:17]
	v_mfma_f32_16x16x32_bf16 v[10:13], v[182:185], v[234:237], v[10:13]
	s_setprio 0
	s_setprio 1
	v_mfma_f32_16x16x32_bf16 v[54:57], v[186:189], v[202:205], v[54:57]
	v_mfma_f32_16x16x32_bf16 v[50:53], v[194:197], v[202:205], v[50:53]
	v_mfma_f32_16x16x32_bf16 v[38:41], v[186:189], v[214:217], v[38:41]
	v_mfma_f32_16x16x32_bf16 v[34:37], v[194:197], v[214:217], v[34:37]
	v_mfma_f32_16x16x32_bf16 v[22:25], v[186:189], v[222:225], v[22:25]
	v_mfma_f32_16x16x32_bf16 v[18:21], v[194:197], v[222:225], v[18:21]
	v_mfma_f32_16x16x32_bf16 v[6:9], v[186:189], v[230:233], v[6:9]
	v_mfma_f32_16x16x32_bf16 v[2:5], v[194:197], v[230:233], v[2:5]
	v_mfma_f32_16x16x32_bf16 v[54:57], v[190:193], v[206:209], v[54:57]
	v_mfma_f32_16x16x32_bf16 v[50:53], v[198:201], v[206:209], v[50:53]
	v_mfma_f32_16x16x32_bf16 v[38:41], v[190:193], v[218:221], v[38:41]
	v_mfma_f32_16x16x32_bf16 v[34:37], v[198:201], v[218:221], v[34:37]
	v_mfma_f32_16x16x32_bf16 v[22:25], v[190:193], v[226:229], v[22:25]
	v_mfma_f32_16x16x32_bf16 v[18:21], v[198:201], v[226:229], v[18:21]
	v_mfma_f32_16x16x32_bf16 v[6:9], v[190:193], v[234:237], v[6:9]
	v_mfma_f32_16x16x32_bf16 v[2:5], v[198:201], v[234:237], v[2:5]
	s_add_i32 s74, s74, 2
	s_add_u32 s72, s72, 0x100
	s_addc_u32 s73, s73, 0
	s_add_u32 s40, s40, 0x100
	s_addc_u32 s41, s41, 0
	s_cmp_gt_u32 s74, 29
	s_setprio 0
	s_cbranch_scc0 .Lg1_head_bar
	s_barrier
	s_and_b64 vcc, exec, s[44:45]
	s_cbranch_vccz .LBB0_421
	s_barrier
